# layer 0 MG->WO completion counters, guarded by grid == 256 (falls back to the grid barrier otherwise)
# speedup vs baseline: 1.0120x; 1.0120x over previous
.Lmgepi_last:
	v_mov_b64_e32 v[210:211], v[214:215]
	global_load_dwordx4 v[144:147], v[210:211], off
	global_load_dwordx4 v[148:151], v[210:211], off offset:256
	s_mov_b64 s[98:99], 0x36000
	v_lshl_add_u64 v[210:211], v[214:215], 0, s[98:99]
	global_load_dwordx4 v[152:155], v[210:211], off
	global_load_dwordx4 v[156:159], v[210:211], off offset:256
	s_mov_b64 s[98:99], 0x6c000
	v_lshl_add_u64 v[210:211], v[214:215], 0, s[98:99]
	global_load_dwordx4 v[160:163], v[210:211], off
	global_load_dwordx4 v[164:167], v[210:211], off offset:256
	s_mov_b64 s[98:99], 0xa2000
	v_lshl_add_u64 v[210:211], v[214:215], 0, s[98:99]
	global_load_dwordx4 v[170:173], v[210:211], off
	global_load_dwordx4 v[174:177], v[210:211], off offset:256
	s_waitcnt vmcnt(0)
	v_mov_b64_e32 v[210:211], v[216:217]
	v_lshlrev_b32_e32 v178, 16, v144
	v_and_b32_e32 v144, 0xffff0000, v144
	v_lshlrev_b32_e32 v179, 16, v145
	v_and_b32_e32 v145, 0xffff0000, v145
	v_lshlrev_b32_e32 v180, 16, v146
	v_and_b32_e32 v146, 0xffff0000, v146
	v_lshlrev_b32_e32 v181, 16, v147
	v_and_b32_e32 v147, 0xffff0000, v147
	v_mul_f32_e32 v178, 0xbfb8aa3b, v178
	v_mul_f32_e32 v144, 0xbfb8aa3b, v144
	v_mul_f32_e32 v179, 0xbfb8aa3b, v179
	v_mul_f32_e32 v145, 0xbfb8aa3b, v145
	v_mul_f32_e32 v180, 0xbfb8aa3b, v180
	v_mul_f32_e32 v146, 0xbfb8aa3b, v146
	v_mul_f32_e32 v181, 0xbfb8aa3b, v181
	v_mul_f32_e32 v147, 0xbfb8aa3b, v147
	v_exp_f32_e32 v178, v178
	v_exp_f32_e32 v144, v144
	v_exp_f32_e32 v179, v179
	v_exp_f32_e32 v145, v145
	v_exp_f32_e32 v180, v180
	v_exp_f32_e32 v146, v146
	v_exp_f32_e32 v181, v181
	v_exp_f32_e32 v147, v147
	v_add_f32_e32 v178, 1.0, v178
	v_add_f32_e32 v144, 1.0, v144
	v_add_f32_e32 v179, 1.0, v179
	v_add_f32_e32 v145, 1.0, v145
	v_add_f32_e32 v180, 1.0, v180
	v_add_f32_e32 v146, 1.0, v146
	v_add_f32_e32 v181, 1.0, v181
	v_add_f32_e32 v147, 1.0, v147
	v_rcp_f32_e32 v178, v178
	v_rcp_f32_e32 v144, v144
	v_rcp_f32_e32 v179, v179
	v_rcp_f32_e32 v145, v145
	v_rcp_f32_e32 v180, v180
	v_rcp_f32_e32 v146, v146
	v_rcp_f32_e32 v181, v181
	v_rcp_f32_e32 v147, v147
	s_nop 0
	v_mul_f32_e32 v186, v128, v178
	v_mul_f32_e32 v187, v129, v144
	v_mul_f32_e32 v188, v130, v179
	v_mul_f32_e32 v189, v131, v145
	v_mul_f32_e32 v190, v124, v180
	v_mul_f32_e32 v191, v125, v146
	v_mul_f32_e32 v192, v126, v181
	v_mul_f32_e32 v193, v127, v147
	v_cvt_pk_bf16_f32 v144, v186, v187
	v_cvt_pk_bf16_f32 v145, v188, v189
	v_cvt_pk_bf16_f32 v146, v190, v191
	v_cvt_pk_bf16_f32 v147, v192, v193
	global_store_dwordx4 v[210:211], v[144:147], off
	v_lshlrev_b32_e32 v178, 16, v148
	v_and_b32_e32 v148, 0xffff0000, v148
	v_lshlrev_b32_e32 v179, 16, v149
	v_and_b32_e32 v149, 0xffff0000, v149
	v_lshlrev_b32_e32 v180, 16, v150
	v_and_b32_e32 v150, 0xffff0000, v150
	v_lshlrev_b32_e32 v181, 16, v151
	v_and_b32_e32 v151, 0xffff0000, v151
	v_mul_f32_e32 v178, 0xbfb8aa3b, v178
	v_mul_f32_e32 v148, 0xbfb8aa3b, v148
	v_mul_f32_e32 v179, 0xbfb8aa3b, v179
	v_mul_f32_e32 v149, 0xbfb8aa3b, v149
	v_mul_f32_e32 v180, 0xbfb8aa3b, v180
	v_mul_f32_e32 v150, 0xbfb8aa3b, v150
	v_mul_f32_e32 v181, 0xbfb8aa3b, v181
	v_mul_f32_e32 v151, 0xbfb8aa3b, v151
	v_exp_f32_e32 v178, v178
	v_exp_f32_e32 v148, v148
	v_exp_f32_e32 v179, v179
	v_exp_f32_e32 v149, v149
	v_exp_f32_e32 v180, v180
	v_exp_f32_e32 v150, v150
	v_exp_f32_e32 v181, v181
	v_exp_f32_e32 v151, v151
	v_add_f32_e32 v178, 1.0, v178
	v_add_f32_e32 v148, 1.0, v148
	v_add_f32_e32 v179, 1.0, v179
	v_add_f32_e32 v149, 1.0, v149
	v_add_f32_e32 v180, 1.0, v180
	v_add_f32_e32 v150, 1.0, v150
	v_add_f32_e32 v181, 1.0, v181
	v_add_f32_e32 v151, 1.0, v151
	v_rcp_f32_e32 v178, v178
	v_rcp_f32_e32 v148, v148
	v_rcp_f32_e32 v179, v179
	v_rcp_f32_e32 v149, v149
	v_rcp_f32_e32 v180, v180
	v_rcp_f32_e32 v150, v150
	v_rcp_f32_e32 v181, v181
	v_rcp_f32_e32 v151, v151
	s_nop 0
	v_mul_f32_e32 v186, v92, v178
	v_mul_f32_e32 v187, v93, v148
	v_mul_f32_e32 v188, v94, v179
	v_mul_f32_e32 v189, v95, v149
	v_mul_f32_e32 v190, v88, v180
	v_mul_f32_e32 v191, v89, v150
	v_mul_f32_e32 v192, v90, v181
	v_mul_f32_e32 v193, v91, v151
	v_cvt_pk_bf16_f32 v148, v186, v187
	v_cvt_pk_bf16_f32 v149, v188, v189
	v_cvt_pk_bf16_f32 v150, v190, v191
	v_cvt_pk_bf16_f32 v151, v192, v193
	global_store_dwordx4 v[210:211], v[148:151], off offset:256
	s_mov_b64 s[98:99], 0x36000
	v_lshl_add_u64 v[210:211], v[216:217], 0, s[98:99]
	v_lshlrev_b32_e32 v178, 16, v152
	v_and_b32_e32 v152, 0xffff0000, v152
	v_lshlrev_b32_e32 v179, 16, v153
	v_and_b32_e32 v153, 0xffff0000, v153
	v_lshlrev_b32_e32 v180, 16, v154
	v_and_b32_e32 v154, 0xffff0000, v154
	v_lshlrev_b32_e32 v181, 16, v155
	v_and_b32_e32 v155, 0xffff0000, v155
	v_mul_f32_e32 v178, 0xbfb8aa3b, v178
	v_mul_f32_e32 v152, 0xbfb8aa3b, v152
	v_mul_f32_e32 v179, 0xbfb8aa3b, v179
	v_mul_f32_e32 v153, 0xbfb8aa3b, v153
	v_mul_f32_e32 v180, 0xbfb8aa3b, v180
	v_mul_f32_e32 v154, 0xbfb8aa3b, v154
	v_mul_f32_e32 v181, 0xbfb8aa3b, v181
	v_mul_f32_e32 v155, 0xbfb8aa3b, v155
	v_exp_f32_e32 v178, v178
	v_exp_f32_e32 v152, v152
	v_exp_f32_e32 v179, v179
	v_exp_f32_e32 v153, v153
	v_exp_f32_e32 v180, v180
	v_exp_f32_e32 v154, v154
	v_exp_f32_e32 v181, v181
	v_exp_f32_e32 v155, v155
	v_add_f32_e32 v178, 1.0, v178
	v_add_f32_e32 v152, 1.0, v152
	v_add_f32_e32 v179, 1.0, v179
	v_add_f32_e32 v153, 1.0, v153
	v_add_f32_e32 v180, 1.0, v180
	v_add_f32_e32 v154, 1.0, v154
	v_add_f32_e32 v181, 1.0, v181
	v_add_f32_e32 v155, 1.0, v155
	v_rcp_f32_e32 v178, v178
	v_rcp_f32_e32 v152, v152
	v_rcp_f32_e32 v179, v179
	v_rcp_f32_e32 v153, v153
	v_rcp_f32_e32 v180, v180
	v_rcp_f32_e32 v154, v154
	v_rcp_f32_e32 v181, v181
	v_rcp_f32_e32 v155, v155
	s_nop 0
	v_mul_f32_e32 v186, v120, v178
	v_mul_f32_e32 v187, v121, v152
	v_mul_f32_e32 v188, v122, v179
	v_mul_f32_e32 v189, v123, v153
	v_mul_f32_e32 v190, v116, v180
	v_mul_f32_e32 v191, v117, v154
	v_mul_f32_e32 v192, v118, v181
	v_mul_f32_e32 v193, v119, v155
	v_cvt_pk_bf16_f32 v152, v186, v187
	v_cvt_pk_bf16_f32 v153, v188, v189
	v_cvt_pk_bf16_f32 v154, v190, v191
	v_cvt_pk_bf16_f32 v155, v192, v193
	global_store_dwordx4 v[210:211], v[152:155], off
	v_lshlrev_b32_e32 v178, 16, v156
	v_and_b32_e32 v156, 0xffff0000, v156
	v_lshlrev_b32_e32 v179, 16, v157
	v_and_b32_e32 v157, 0xffff0000, v157
	v_lshlrev_b32_e32 v180, 16, v158
	v_and_b32_e32 v158, 0xffff0000, v158
	v_lshlrev_b32_e32 v181, 16, v159
	v_and_b32_e32 v159, 0xffff0000, v159
	v_mul_f32_e32 v178, 0xbfb8aa3b, v178
	v_mul_f32_e32 v156, 0xbfb8aa3b, v156
	v_mul_f32_e32 v179, 0xbfb8aa3b, v179
	v_mul_f32_e32 v157, 0xbfb8aa3b, v157
	v_mul_f32_e32 v180, 0xbfb8aa3b, v180
	v_mul_f32_e32 v158, 0xbfb8aa3b, v158
	v_mul_f32_e32 v181, 0xbfb8aa3b, v181
	v_mul_f32_e32 v159, 0xbfb8aa3b, v159
	v_exp_f32_e32 v178, v178
	v_exp_f32_e32 v156, v156
	v_exp_f32_e32 v179, v179
	v_exp_f32_e32 v157, v157
	v_exp_f32_e32 v180, v180
	v_exp_f32_e32 v158, v158
	v_exp_f32_e32 v181, v181
	v_exp_f32_e32 v159, v159
	v_add_f32_e32 v178, 1.0, v178
	v_add_f32_e32 v156, 1.0, v156
	v_add_f32_e32 v179, 1.0, v179
	v_add_f32_e32 v157, 1.0, v157
	v_add_f32_e32 v180, 1.0, v180
	v_add_f32_e32 v158, 1.0, v158
	v_add_f32_e32 v181, 1.0, v181
	v_add_f32_e32 v159, 1.0, v159
	v_rcp_f32_e32 v178, v178
	v_rcp_f32_e32 v156, v156
	v_rcp_f32_e32 v179, v179
	v_rcp_f32_e32 v157, v157
	v_rcp_f32_e32 v180, v180
	v_rcp_f32_e32 v158, v158
	v_rcp_f32_e32 v181, v181
	v_rcp_f32_e32 v159, v159
	s_nop 0
	v_mul_f32_e32 v186, v84, v178
	v_mul_f32_e32 v187, v85, v156
	v_mul_f32_e32 v188, v86, v179
	v_mul_f32_e32 v189, v87, v157
	v_mul_f32_e32 v190, v80, v180
	v_mul_f32_e32 v191, v81, v158
	v_mul_f32_e32 v192, v82, v181
	v_mul_f32_e32 v193, v83, v159
	v_cvt_pk_bf16_f32 v156, v186, v187
	v_cvt_pk_bf16_f32 v157, v188, v189
	v_cvt_pk_bf16_f32 v158, v190, v191
	v_cvt_pk_bf16_f32 v159, v192, v193
	global_store_dwordx4 v[210:211], v[156:159], off offset:256
	s_mov_b64 s[98:99], 0x6c000
	v_lshl_add_u64 v[210:211], v[216:217], 0, s[98:99]
	v_lshlrev_b32_e32 v178, 16, v160
	v_and_b32_e32 v160, 0xffff0000, v160
	v_lshlrev_b32_e32 v179, 16, v161
	v_and_b32_e32 v161, 0xffff0000, v161
	v_lshlrev_b32_e32 v180, 16, v162
	v_and_b32_e32 v162, 0xffff0000, v162
	v_lshlrev_b32_e32 v181, 16, v163
	v_and_b32_e32 v163, 0xffff0000, v163
	v_mul_f32_e32 v178, 0xbfb8aa3b, v178
	v_mul_f32_e32 v160, 0xbfb8aa3b, v160
	v_mul_f32_e32 v179, 0xbfb8aa3b, v179
	v_mul_f32_e32 v161, 0xbfb8aa3b, v161
	v_mul_f32_e32 v180, 0xbfb8aa3b, v180
	v_mul_f32_e32 v162, 0xbfb8aa3b, v162
	v_mul_f32_e32 v181, 0xbfb8aa3b, v181
	v_mul_f32_e32 v163, 0xbfb8aa3b, v163
	v_exp_f32_e32 v178, v178
	v_exp_f32_e32 v160, v160
	v_exp_f32_e32 v179, v179
	v_exp_f32_e32 v161, v161
	v_exp_f32_e32 v180, v180
	v_exp_f32_e32 v162, v162
	v_exp_f32_e32 v181, v181
	v_exp_f32_e32 v163, v163
	v_add_f32_e32 v178, 1.0, v178
	v_add_f32_e32 v160, 1.0, v160
	v_add_f32_e32 v179, 1.0, v179
	v_add_f32_e32 v161, 1.0, v161
	v_add_f32_e32 v180, 1.0, v180
	v_add_f32_e32 v162, 1.0, v162
	v_add_f32_e32 v181, 1.0, v181
	v_add_f32_e32 v163, 1.0, v163
	v_rcp_f32_e32 v178, v178
	v_rcp_f32_e32 v160, v160
	v_rcp_f32_e32 v179, v179
	v_rcp_f32_e32 v161, v161
	v_rcp_f32_e32 v180, v180
	v_rcp_f32_e32 v162, v162
	v_rcp_f32_e32 v181, v181
	v_rcp_f32_e32 v163, v163
	s_nop 0
	v_mul_f32_e32 v186, v108, v178
	v_mul_f32_e32 v187, v109, v160
	v_mul_f32_e32 v188, v110, v179
	v_mul_f32_e32 v189, v111, v161
	v_mul_f32_e32 v190, v104, v180
	v_mul_f32_e32 v191, v105, v162
	v_mul_f32_e32 v192, v106, v181
	v_mul_f32_e32 v193, v107, v163
	v_cvt_pk_bf16_f32 v160, v186, v187
	v_cvt_pk_bf16_f32 v161, v188, v189
	v_cvt_pk_bf16_f32 v162, v190, v191
	v_cvt_pk_bf16_f32 v163, v192, v193
	global_store_dwordx4 v[210:211], v[160:163], off
	v_lshlrev_b32_e32 v178, 16, v164
	v_and_b32_e32 v164, 0xffff0000, v164
	v_lshlrev_b32_e32 v179, 16, v165
	v_and_b32_e32 v165, 0xffff0000, v165
	v_lshlrev_b32_e32 v180, 16, v166
	v_and_b32_e32 v166, 0xffff0000, v166
	v_lshlrev_b32_e32 v181, 16, v167
	v_and_b32_e32 v167, 0xffff0000, v167
	v_mul_f32_e32 v178, 0xbfb8aa3b, v178
	v_mul_f32_e32 v164, 0xbfb8aa3b, v164
	v_mul_f32_e32 v179, 0xbfb8aa3b, v179
	v_mul_f32_e32 v165, 0xbfb8aa3b, v165
	v_mul_f32_e32 v180, 0xbfb8aa3b, v180
	v_mul_f32_e32 v166, 0xbfb8aa3b, v166
	v_mul_f32_e32 v181, 0xbfb8aa3b, v181
	v_mul_f32_e32 v167, 0xbfb8aa3b, v167
	v_exp_f32_e32 v178, v178
	v_exp_f32_e32 v164, v164
	v_exp_f32_e32 v179, v179
	v_exp_f32_e32 v165, v165
	v_exp_f32_e32 v180, v180
	v_exp_f32_e32 v166, v166
	v_exp_f32_e32 v181, v181
	v_exp_f32_e32 v167, v167
	v_add_f32_e32 v178, 1.0, v178
	v_add_f32_e32 v164, 1.0, v164
	v_add_f32_e32 v179, 1.0, v179
	v_add_f32_e32 v165, 1.0, v165
	v_add_f32_e32 v180, 1.0, v180
	v_add_f32_e32 v166, 1.0, v166
	v_add_f32_e32 v181, 1.0, v181
	v_add_f32_e32 v167, 1.0, v167
	v_rcp_f32_e32 v178, v178
	v_rcp_f32_e32 v164, v164
	v_rcp_f32_e32 v179, v179
	v_rcp_f32_e32 v165, v165
	v_rcp_f32_e32 v180, v180
	v_rcp_f32_e32 v166, v166
	v_rcp_f32_e32 v181, v181
	v_rcp_f32_e32 v167, v167
	s_nop 0
	v_mul_f32_e32 v186, v76, v178
	v_mul_f32_e32 v187, v77, v164
	v_mul_f32_e32 v188, v78, v179
	v_mul_f32_e32 v189, v79, v165
	v_mul_f32_e32 v190, v72, v180
	v_mul_f32_e32 v191, v73, v166
	v_mul_f32_e32 v192, v74, v181
	v_mul_f32_e32 v193, v75, v167
	v_cvt_pk_bf16_f32 v164, v186, v187
	v_cvt_pk_bf16_f32 v165, v188, v189
	v_cvt_pk_bf16_f32 v166, v190, v191
	v_cvt_pk_bf16_f32 v167, v192, v193
	global_store_dwordx4 v[210:211], v[164:167], off offset:256
	s_mov_b64 s[98:99], 0xa2000
	v_lshl_add_u64 v[210:211], v[216:217], 0, s[98:99]
	v_lshlrev_b32_e32 v178, 16, v170
	v_and_b32_e32 v170, 0xffff0000, v170
	v_lshlrev_b32_e32 v179, 16, v171
	v_and_b32_e32 v171, 0xffff0000, v171
	v_lshlrev_b32_e32 v180, 16, v172
	v_and_b32_e32 v172, 0xffff0000, v172
	v_lshlrev_b32_e32 v181, 16, v173
	v_and_b32_e32 v173, 0xffff0000, v173
	v_mul_f32_e32 v178, 0xbfb8aa3b, v178
	v_mul_f32_e32 v170, 0xbfb8aa3b, v170
	v_mul_f32_e32 v179, 0xbfb8aa3b, v179
	v_mul_f32_e32 v171, 0xbfb8aa3b, v171
	v_mul_f32_e32 v180, 0xbfb8aa3b, v180
	v_mul_f32_e32 v172, 0xbfb8aa3b, v172
	v_mul_f32_e32 v181, 0xbfb8aa3b, v181
	v_mul_f32_e32 v173, 0xbfb8aa3b, v173
	v_exp_f32_e32 v178, v178
	v_exp_f32_e32 v170, v170
	v_exp_f32_e32 v179, v179
	v_exp_f32_e32 v171, v171
	v_exp_f32_e32 v180, v180
	v_exp_f32_e32 v172, v172
	v_exp_f32_e32 v181, v181
	v_exp_f32_e32 v173, v173
	v_add_f32_e32 v178, 1.0, v178
	v_add_f32_e32 v170, 1.0, v170
	v_add_f32_e32 v179, 1.0, v179
	v_add_f32_e32 v171, 1.0, v171
	v_add_f32_e32 v180, 1.0, v180
	v_add_f32_e32 v172, 1.0, v172
	v_add_f32_e32 v181, 1.0, v181
	v_add_f32_e32 v173, 1.0, v173
	v_rcp_f32_e32 v178, v178
	v_rcp_f32_e32 v170, v170
	v_rcp_f32_e32 v179, v179
	v_rcp_f32_e32 v171, v171
	v_rcp_f32_e32 v180, v180
	v_rcp_f32_e32 v172, v172
	v_rcp_f32_e32 v181, v181
	v_rcp_f32_e32 v173, v173
	s_nop 0
	v_mul_f32_e32 v186, v100, v178
	v_mul_f32_e32 v187, v101, v170
	v_mul_f32_e32 v188, v102, v179
	v_mul_f32_e32 v189, v103, v171
	v_mul_f32_e32 v190, v96, v180
	v_mul_f32_e32 v191, v97, v172
	v_mul_f32_e32 v192, v98, v181
	v_mul_f32_e32 v193, v99, v173
	v_cvt_pk_bf16_f32 v170, v186, v187
	v_cvt_pk_bf16_f32 v171, v188, v189
	v_cvt_pk_bf16_f32 v172, v190, v191
	v_cvt_pk_bf16_f32 v173, v192, v193
	global_store_dwordx4 v[210:211], v[170:173], off
	v_lshlrev_b32_e32 v178, 16, v174
	v_and_b32_e32 v174, 0xffff0000, v174
	v_lshlrev_b32_e32 v179, 16, v175
	v_and_b32_e32 v175, 0xffff0000, v175
	v_lshlrev_b32_e32 v180, 16, v176
	v_and_b32_e32 v176, 0xffff0000, v176
	v_lshlrev_b32_e32 v181, 16, v177
	v_and_b32_e32 v177, 0xffff0000, v177
	v_mul_f32_e32 v178, 0xbfb8aa3b, v178
	v_mul_f32_e32 v174, 0xbfb8aa3b, v174
	v_mul_f32_e32 v179, 0xbfb8aa3b, v179
	v_mul_f32_e32 v175, 0xbfb8aa3b, v175
	v_mul_f32_e32 v180, 0xbfb8aa3b, v180
	v_mul_f32_e32 v176, 0xbfb8aa3b, v176
	v_mul_f32_e32 v181, 0xbfb8aa3b, v181
	v_mul_f32_e32 v177, 0xbfb8aa3b, v177
	v_exp_f32_e32 v178, v178
	v_exp_f32_e32 v174, v174
	v_exp_f32_e32 v179, v179
	v_exp_f32_e32 v175, v175
	v_exp_f32_e32 v180, v180
	v_exp_f32_e32 v176, v176
	v_exp_f32_e32 v181, v181
	v_exp_f32_e32 v177, v177
	v_add_f32_e32 v178, 1.0, v178
	v_add_f32_e32 v174, 1.0, v174
	v_add_f32_e32 v179, 1.0, v179
	v_add_f32_e32 v175, 1.0, v175
	v_add_f32_e32 v180, 1.0, v180
	v_add_f32_e32 v176, 1.0, v176
	v_add_f32_e32 v181, 1.0, v181
	v_add_f32_e32 v177, 1.0, v177
	v_rcp_f32_e32 v178, v178
	v_rcp_f32_e32 v174, v174
	v_rcp_f32_e32 v179, v179
	v_rcp_f32_e32 v175, v175
	v_rcp_f32_e32 v180, v180
	v_rcp_f32_e32 v176, v176
	v_rcp_f32_e32 v181, v181
	v_rcp_f32_e32 v177, v177
	s_nop 0
	v_mul_f32_e32 v186, v68, v178
	v_mul_f32_e32 v187, v69, v174
	v_mul_f32_e32 v188, v70, v179
	v_mul_f32_e32 v189, v71, v175
	v_mul_f32_e32 v190, v64, v180
	v_mul_f32_e32 v191, v65, v176
	v_mul_f32_e32 v192, v66, v181
	v_mul_f32_e32 v193, v67, v177
	v_cvt_pk_bf16_f32 v174, v186, v187
	v_cvt_pk_bf16_f32 v175, v188, v189
	v_cvt_pk_bf16_f32 v176, v190, v191
	v_cvt_pk_bf16_f32 v177, v192, v193
	global_store_dwordx4 v[210:211], v[174:177], off offset:256
	s_mov_b64 s[98:99], 0x1b0000
	v_lshl_add_u64 v[210:211], v[214:215], 0, s[98:99]
	global_load_dwordx4 v[144:147], v[210:211], off
	global_load_dwordx4 v[148:151], v[210:211], off offset:256
	s_mov_b64 s[98:99], 0x1e6000
	v_lshl_add_u64 v[210:211], v[214:215], 0, s[98:99]
	global_load_dwordx4 v[152:155], v[210:211], off
	global_load_dwordx4 v[156:159], v[210:211], off offset:256
	s_mov_b64 s[98:99], 0x21c000
	v_lshl_add_u64 v[210:211], v[214:215], 0, s[98:99]
	global_load_dwordx4 v[160:163], v[210:211], off
	global_load_dwordx4 v[164:167], v[210:211], off offset:256
	s_mov_b64 s[98:99], 0x252000
	v_lshl_add_u64 v[210:211], v[214:215], 0, s[98:99]
	global_load_dwordx4 v[170:173], v[210:211], off
	global_load_dwordx4 v[174:177], v[210:211], off offset:256
	s_waitcnt vmcnt(0)
	s_mov_b64 s[98:99], 0x1b0000
	v_lshl_add_u64 v[210:211], v[216:217], 0, s[98:99]
	v_lshlrev_b32_e32 v178, 16, v144
	v_and_b32_e32 v144, 0xffff0000, v144
	v_lshlrev_b32_e32 v179, 16, v145
	v_and_b32_e32 v145, 0xffff0000, v145
	v_lshlrev_b32_e32 v180, 16, v146
	v_and_b32_e32 v146, 0xffff0000, v146
	v_lshlrev_b32_e32 v181, 16, v147
	v_and_b32_e32 v147, 0xffff0000, v147
	v_mul_f32_e32 v178, 0xbfb8aa3b, v178
	v_mul_f32_e32 v144, 0xbfb8aa3b, v144
	v_mul_f32_e32 v179, 0xbfb8aa3b, v179
	v_mul_f32_e32 v145, 0xbfb8aa3b, v145
	v_mul_f32_e32 v180, 0xbfb8aa3b, v180
	v_mul_f32_e32 v146, 0xbfb8aa3b, v146
	v_mul_f32_e32 v181, 0xbfb8aa3b, v181
	v_mul_f32_e32 v147, 0xbfb8aa3b, v147
	v_exp_f32_e32 v178, v178
	v_exp_f32_e32 v144, v144
	v_exp_f32_e32 v179, v179
	v_exp_f32_e32 v145, v145
	v_exp_f32_e32 v180, v180
	v_exp_f32_e32 v146, v146
	v_exp_f32_e32 v181, v181
	v_exp_f32_e32 v147, v147
	v_add_f32_e32 v178, 1.0, v178
	v_add_f32_e32 v144, 1.0, v144
	v_add_f32_e32 v179, 1.0, v179
	v_add_f32_e32 v145, 1.0, v145
	v_add_f32_e32 v180, 1.0, v180
	v_add_f32_e32 v146, 1.0, v146
	v_add_f32_e32 v181, 1.0, v181
	v_add_f32_e32 v147, 1.0, v147
	v_rcp_f32_e32 v178, v178
	v_rcp_f32_e32 v144, v144
	v_rcp_f32_e32 v179, v179
	v_rcp_f32_e32 v145, v145
	v_rcp_f32_e32 v180, v180
	v_rcp_f32_e32 v146, v146
	v_rcp_f32_e32 v181, v181
	v_rcp_f32_e32 v147, v147
	s_nop 0
	v_mul_f32_e32 v186, v60, v178
	v_mul_f32_e32 v187, v61, v144
	v_mul_f32_e32 v188, v62, v179
	v_mul_f32_e32 v189, v63, v145
	v_mul_f32_e32 v190, v56, v180
	v_mul_f32_e32 v191, v57, v146
	v_mul_f32_e32 v192, v58, v181
	v_mul_f32_e32 v193, v59, v147
	v_cvt_pk_bf16_f32 v144, v186, v187
	v_cvt_pk_bf16_f32 v145, v188, v189
	v_cvt_pk_bf16_f32 v146, v190, v191
	v_cvt_pk_bf16_f32 v147, v192, v193
	global_store_dwordx4 v[210:211], v[144:147], off
	v_lshlrev_b32_e32 v178, 16, v148
	v_and_b32_e32 v148, 0xffff0000, v148
	v_lshlrev_b32_e32 v179, 16, v149
	v_and_b32_e32 v149, 0xffff0000, v149
	v_lshlrev_b32_e32 v180, 16, v150
	v_and_b32_e32 v150, 0xffff0000, v150
	v_lshlrev_b32_e32 v181, 16, v151
	v_and_b32_e32 v151, 0xffff0000, v151
	v_mul_f32_e32 v178, 0xbfb8aa3b, v178
	v_mul_f32_e32 v148, 0xbfb8aa3b, v148
	v_mul_f32_e32 v179, 0xbfb8aa3b, v179
	v_mul_f32_e32 v149, 0xbfb8aa3b, v149
	v_mul_f32_e32 v180, 0xbfb8aa3b, v180
	v_mul_f32_e32 v150, 0xbfb8aa3b, v150
	v_mul_f32_e32 v181, 0xbfb8aa3b, v181
	v_mul_f32_e32 v151, 0xbfb8aa3b, v151
	v_exp_f32_e32 v178, v178
	v_exp_f32_e32 v148, v148
	v_exp_f32_e32 v179, v179
	v_exp_f32_e32 v149, v149
	v_exp_f32_e32 v180, v180
	v_exp_f32_e32 v150, v150
	v_exp_f32_e32 v181, v181
	v_exp_f32_e32 v151, v151
	v_add_f32_e32 v178, 1.0, v178
	v_add_f32_e32 v148, 1.0, v148
	v_add_f32_e32 v179, 1.0, v179
	v_add_f32_e32 v149, 1.0, v149
	v_add_f32_e32 v180, 1.0, v180
	v_add_f32_e32 v150, 1.0, v150
	v_add_f32_e32 v181, 1.0, v181
	v_add_f32_e32 v151, 1.0, v151
	v_rcp_f32_e32 v178, v178
	v_rcp_f32_e32 v148, v148
	v_rcp_f32_e32 v179, v179
	v_rcp_f32_e32 v149, v149
	v_rcp_f32_e32 v180, v180
	v_rcp_f32_e32 v150, v150
	v_rcp_f32_e32 v181, v181
	v_rcp_f32_e32 v151, v151
	s_nop 0
	v_mul_f32_e32 v186, v28, v178
	v_mul_f32_e32 v187, v29, v148
	v_mul_f32_e32 v188, v30, v179
	v_mul_f32_e32 v189, v31, v149
	v_mul_f32_e32 v190, v24, v180
	v_mul_f32_e32 v191, v25, v150
	v_mul_f32_e32 v192, v26, v181
	v_mul_f32_e32 v193, v27, v151
	v_cvt_pk_bf16_f32 v148, v186, v187
	v_cvt_pk_bf16_f32 v149, v188, v189
	v_cvt_pk_bf16_f32 v150, v190, v191
	v_cvt_pk_bf16_f32 v151, v192, v193
	global_store_dwordx4 v[210:211], v[148:151], off offset:256
	s_mov_b64 s[98:99], 0x1e6000
	v_lshl_add_u64 v[210:211], v[216:217], 0, s[98:99]
	v_lshlrev_b32_e32 v178, 16, v152
	v_and_b32_e32 v152, 0xffff0000, v152
	v_lshlrev_b32_e32 v179, 16, v153
	v_and_b32_e32 v153, 0xffff0000, v153
	v_lshlrev_b32_e32 v180, 16, v154
	v_and_b32_e32 v154, 0xffff0000, v154
	v_lshlrev_b32_e32 v181, 16, v155
	v_and_b32_e32 v155, 0xffff0000, v155
	v_mul_f32_e32 v178, 0xbfb8aa3b, v178
	v_mul_f32_e32 v152, 0xbfb8aa3b, v152
	v_mul_f32_e32 v179, 0xbfb8aa3b, v179
	v_mul_f32_e32 v153, 0xbfb8aa3b, v153
	v_mul_f32_e32 v180, 0xbfb8aa3b, v180
	v_mul_f32_e32 v154, 0xbfb8aa3b, v154
	v_mul_f32_e32 v181, 0xbfb8aa3b, v181
	v_mul_f32_e32 v155, 0xbfb8aa3b, v155
	v_exp_f32_e32 v178, v178
	v_exp_f32_e32 v152, v152
	v_exp_f32_e32 v179, v179
	v_exp_f32_e32 v153, v153
	v_exp_f32_e32 v180, v180
	v_exp_f32_e32 v154, v154
	v_exp_f32_e32 v181, v181
	v_exp_f32_e32 v155, v155
	v_add_f32_e32 v178, 1.0, v178
	v_add_f32_e32 v152, 1.0, v152
	v_add_f32_e32 v179, 1.0, v179
	v_add_f32_e32 v153, 1.0, v153
	v_add_f32_e32 v180, 1.0, v180
	v_add_f32_e32 v154, 1.0, v154
	v_add_f32_e32 v181, 1.0, v181
	v_add_f32_e32 v155, 1.0, v155
	v_rcp_f32_e32 v178, v178
	v_rcp_f32_e32 v152, v152
	v_rcp_f32_e32 v179, v179
	v_rcp_f32_e32 v153, v153
	v_rcp_f32_e32 v180, v180
	v_rcp_f32_e32 v154, v154
	v_rcp_f32_e32 v181, v181
	v_rcp_f32_e32 v155, v155
	s_nop 0
	v_mul_f32_e32 v186, v52, v178
	v_mul_f32_e32 v187, v53, v152
	v_mul_f32_e32 v188, v54, v179
	v_mul_f32_e32 v189, v55, v153
	v_mul_f32_e32 v190, v48, v180
	v_mul_f32_e32 v191, v49, v154
	v_mul_f32_e32 v192, v50, v181
	v_mul_f32_e32 v193, v51, v155
	v_cvt_pk_bf16_f32 v152, v186, v187
	v_cvt_pk_bf16_f32 v153, v188, v189
	v_cvt_pk_bf16_f32 v154, v190, v191
	v_cvt_pk_bf16_f32 v155, v192, v193
	global_store_dwordx4 v[210:211], v[152:155], off
	v_lshlrev_b32_e32 v178, 16, v156
	v_and_b32_e32 v156, 0xffff0000, v156
	v_lshlrev_b32_e32 v179, 16, v157
	v_and_b32_e32 v157, 0xffff0000, v157
	v_lshlrev_b32_e32 v180, 16, v158
	v_and_b32_e32 v158, 0xffff0000, v158
	v_lshlrev_b32_e32 v181, 16, v159
	v_and_b32_e32 v159, 0xffff0000, v159
	v_mul_f32_e32 v178, 0xbfb8aa3b, v178
	v_mul_f32_e32 v156, 0xbfb8aa3b, v156
	v_mul_f32_e32 v179, 0xbfb8aa3b, v179
	v_mul_f32_e32 v157, 0xbfb8aa3b, v157
	v_mul_f32_e32 v180, 0xbfb8aa3b, v180
	v_mul_f32_e32 v158, 0xbfb8aa3b, v158
	v_mul_f32_e32 v181, 0xbfb8aa3b, v181
	v_mul_f32_e32 v159, 0xbfb8aa3b, v159
	v_exp_f32_e32 v178, v178
	v_exp_f32_e32 v156, v156
	v_exp_f32_e32 v179, v179
	v_exp_f32_e32 v157, v157
	v_exp_f32_e32 v180, v180
	v_exp_f32_e32 v158, v158
	v_exp_f32_e32 v181, v181
	v_exp_f32_e32 v159, v159
	v_add_f32_e32 v178, 1.0, v178
	v_add_f32_e32 v156, 1.0, v156
	v_add_f32_e32 v179, 1.0, v179
	v_add_f32_e32 v157, 1.0, v157
	v_add_f32_e32 v180, 1.0, v180
	v_add_f32_e32 v158, 1.0, v158
	v_add_f32_e32 v181, 1.0, v181
	v_add_f32_e32 v159, 1.0, v159
	v_rcp_f32_e32 v178, v178
	v_rcp_f32_e32 v156, v156
	v_rcp_f32_e32 v179, v179
	v_rcp_f32_e32 v157, v157
	v_rcp_f32_e32 v180, v180
	v_rcp_f32_e32 v158, v158
	v_rcp_f32_e32 v181, v181
	v_rcp_f32_e32 v159, v159
	s_nop 0
	v_mul_f32_e32 v186, v20, v178
	v_mul_f32_e32 v187, v21, v156
	v_mul_f32_e32 v188, v22, v179
	v_mul_f32_e32 v189, v23, v157
	v_mul_f32_e32 v190, v16, v180
	v_mul_f32_e32 v191, v17, v158
	v_mul_f32_e32 v192, v18, v181
	v_mul_f32_e32 v193, v19, v159
	v_cvt_pk_bf16_f32 v156, v186, v187
	v_cvt_pk_bf16_f32 v157, v188, v189
	v_cvt_pk_bf16_f32 v158, v190, v191
	v_cvt_pk_bf16_f32 v159, v192, v193
	global_store_dwordx4 v[210:211], v[156:159], off offset:256
	s_mov_b64 s[98:99], 0x21c000
	v_lshl_add_u64 v[210:211], v[216:217], 0, s[98:99]
	v_lshlrev_b32_e32 v178, 16, v160
	v_and_b32_e32 v160, 0xffff0000, v160
	v_lshlrev_b32_e32 v179, 16, v161
	v_and_b32_e32 v161, 0xffff0000, v161
	v_lshlrev_b32_e32 v180, 16, v162
	v_and_b32_e32 v162, 0xffff0000, v162
	v_lshlrev_b32_e32 v181, 16, v163
	v_and_b32_e32 v163, 0xffff0000, v163
	v_mul_f32_e32 v178, 0xbfb8aa3b, v178
	v_mul_f32_e32 v160, 0xbfb8aa3b, v160
	v_mul_f32_e32 v179, 0xbfb8aa3b, v179
	v_mul_f32_e32 v161, 0xbfb8aa3b, v161
	v_mul_f32_e32 v180, 0xbfb8aa3b, v180
	v_mul_f32_e32 v162, 0xbfb8aa3b, v162
	v_mul_f32_e32 v181, 0xbfb8aa3b, v181
	v_mul_f32_e32 v163, 0xbfb8aa3b, v163
	v_exp_f32_e32 v178, v178
	v_exp_f32_e32 v160, v160
	v_exp_f32_e32 v179, v179
	v_exp_f32_e32 v161, v161
	v_exp_f32_e32 v180, v180
	v_exp_f32_e32 v162, v162
	v_exp_f32_e32 v181, v181
	v_exp_f32_e32 v163, v163
	v_add_f32_e32 v178, 1.0, v178
	v_add_f32_e32 v160, 1.0, v160
	v_add_f32_e32 v179, 1.0, v179
	v_add_f32_e32 v161, 1.0, v161
	v_add_f32_e32 v180, 1.0, v180
	v_add_f32_e32 v162, 1.0, v162
	v_add_f32_e32 v181, 1.0, v181
	v_add_f32_e32 v163, 1.0, v163
	v_rcp_f32_e32 v178, v178
	v_rcp_f32_e32 v160, v160
	v_rcp_f32_e32 v179, v179
	v_rcp_f32_e32 v161, v161
	v_rcp_f32_e32 v180, v180
	v_rcp_f32_e32 v162, v162
	v_rcp_f32_e32 v181, v181
	v_rcp_f32_e32 v163, v163
	s_nop 0
	v_mul_f32_e32 v186, v44, v178
	v_mul_f32_e32 v187, v45, v160
	v_mul_f32_e32 v188, v46, v179
	v_mul_f32_e32 v189, v47, v161
	v_mul_f32_e32 v190, v40, v180
	v_mul_f32_e32 v191, v41, v162
	v_mul_f32_e32 v192, v42, v181
	v_mul_f32_e32 v193, v43, v163
	v_cvt_pk_bf16_f32 v160, v186, v187
	v_cvt_pk_bf16_f32 v161, v188, v189
	v_cvt_pk_bf16_f32 v162, v190, v191
	v_cvt_pk_bf16_f32 v163, v192, v193
	global_store_dwordx4 v[210:211], v[160:163], off
	v_lshlrev_b32_e32 v178, 16, v164
	v_and_b32_e32 v164, 0xffff0000, v164
	v_lshlrev_b32_e32 v179, 16, v165
	v_and_b32_e32 v165, 0xffff0000, v165
	v_lshlrev_b32_e32 v180, 16, v166
	v_and_b32_e32 v166, 0xffff0000, v166
	v_lshlrev_b32_e32 v181, 16, v167
	v_and_b32_e32 v167, 0xffff0000, v167
	v_mul_f32_e32 v178, 0xbfb8aa3b, v178
	v_mul_f32_e32 v164, 0xbfb8aa3b, v164
	v_mul_f32_e32 v179, 0xbfb8aa3b, v179
	v_mul_f32_e32 v165, 0xbfb8aa3b, v165
	v_mul_f32_e32 v180, 0xbfb8aa3b, v180
	v_mul_f32_e32 v166, 0xbfb8aa3b, v166
	v_mul_f32_e32 v181, 0xbfb8aa3b, v181
	v_mul_f32_e32 v167, 0xbfb8aa3b, v167
	v_exp_f32_e32 v178, v178
	v_exp_f32_e32 v164, v164
	v_exp_f32_e32 v179, v179
	v_exp_f32_e32 v165, v165
	v_exp_f32_e32 v180, v180
	v_exp_f32_e32 v166, v166
	v_exp_f32_e32 v181, v181
	v_exp_f32_e32 v167, v167
	v_add_f32_e32 v178, 1.0, v178
	v_add_f32_e32 v164, 1.0, v164
	v_add_f32_e32 v179, 1.0, v179
	v_add_f32_e32 v165, 1.0, v165
	v_add_f32_e32 v180, 1.0, v180
	v_add_f32_e32 v166, 1.0, v166
	v_add_f32_e32 v181, 1.0, v181
	v_add_f32_e32 v167, 1.0, v167
	v_rcp_f32_e32 v178, v178
	v_rcp_f32_e32 v164, v164
	v_rcp_f32_e32 v179, v179
	v_rcp_f32_e32 v165, v165
	v_rcp_f32_e32 v180, v180
	v_rcp_f32_e32 v166, v166
	v_rcp_f32_e32 v181, v181
	v_rcp_f32_e32 v167, v167
	s_nop 0
	v_mul_f32_e32 v186, v12, v178
	v_mul_f32_e32 v187, v13, v164
	v_mul_f32_e32 v188, v14, v179
	v_mul_f32_e32 v189, v15, v165
	v_mul_f32_e32 v190, v8, v180
	v_mul_f32_e32 v191, v9, v166
	v_mul_f32_e32 v192, v10, v181
	v_mul_f32_e32 v193, v11, v167
	v_cvt_pk_bf16_f32 v164, v186, v187
	v_cvt_pk_bf16_f32 v165, v188, v189
	v_cvt_pk_bf16_f32 v166, v190, v191
	v_cvt_pk_bf16_f32 v167, v192, v193
	global_store_dwordx4 v[210:211], v[164:167], off offset:256
	s_mov_b64 s[98:99], 0x252000
	v_lshl_add_u64 v[210:211], v[216:217], 0, s[98:99]
	v_lshlrev_b32_e32 v178, 16, v170
	v_and_b32_e32 v170, 0xffff0000, v170
	v_lshlrev_b32_e32 v179, 16, v171
	v_and_b32_e32 v171, 0xffff0000, v171
	v_lshlrev_b32_e32 v180, 16, v172
	v_and_b32_e32 v172, 0xffff0000, v172
	v_lshlrev_b32_e32 v181, 16, v173
	v_and_b32_e32 v173, 0xffff0000, v173
	v_mul_f32_e32 v178, 0xbfb8aa3b, v178
	v_mul_f32_e32 v170, 0xbfb8aa3b, v170
	v_mul_f32_e32 v179, 0xbfb8aa3b, v179
	v_mul_f32_e32 v171, 0xbfb8aa3b, v171
	v_mul_f32_e32 v180, 0xbfb8aa3b, v180
	v_mul_f32_e32 v172, 0xbfb8aa3b, v172
	v_mul_f32_e32 v181, 0xbfb8aa3b, v181
	v_mul_f32_e32 v173, 0xbfb8aa3b, v173
	v_exp_f32_e32 v178, v178
	v_exp_f32_e32 v170, v170
	v_exp_f32_e32 v179, v179
	v_exp_f32_e32 v171, v171
	v_exp_f32_e32 v180, v180
	v_exp_f32_e32 v172, v172
	v_exp_f32_e32 v181, v181
	v_exp_f32_e32 v173, v173
	v_add_f32_e32 v178, 1.0, v178
	v_add_f32_e32 v170, 1.0, v170
	v_add_f32_e32 v179, 1.0, v179
	v_add_f32_e32 v171, 1.0, v171
	v_add_f32_e32 v180, 1.0, v180
	v_add_f32_e32 v172, 1.0, v172
	v_add_f32_e32 v181, 1.0, v181
	v_add_f32_e32 v173, 1.0, v173
	v_rcp_f32_e32 v178, v178
	v_rcp_f32_e32 v170, v170
	v_rcp_f32_e32 v179, v179
	v_rcp_f32_e32 v171, v171
	v_rcp_f32_e32 v180, v180
	v_rcp_f32_e32 v172, v172
	v_rcp_f32_e32 v181, v181
	v_rcp_f32_e32 v173, v173
	s_nop 0
	v_mul_f32_e32 v186, v36, v178
	v_mul_f32_e32 v187, v37, v170
	v_mul_f32_e32 v188, v38, v179
	v_mul_f32_e32 v189, v39, v171
	v_mul_f32_e32 v190, v32, v180
	v_mul_f32_e32 v191, v33, v172
	v_mul_f32_e32 v192, v34, v181
	v_mul_f32_e32 v193, v35, v173
	v_cvt_pk_bf16_f32 v170, v186, v187
	v_cvt_pk_bf16_f32 v171, v188, v189
	v_cvt_pk_bf16_f32 v172, v190, v191
	v_cvt_pk_bf16_f32 v173, v192, v193
	global_store_dwordx4 v[210:211], v[170:173], off
	v_lshlrev_b32_e32 v178, 16, v174
	v_and_b32_e32 v174, 0xffff0000, v174
	v_lshlrev_b32_e32 v179, 16, v175
	v_and_b32_e32 v175, 0xffff0000, v175
	v_lshlrev_b32_e32 v180, 16, v176
	v_and_b32_e32 v176, 0xffff0000, v176
	v_lshlrev_b32_e32 v181, 16, v177
	v_and_b32_e32 v177, 0xffff0000, v177
	v_mul_f32_e32 v178, 0xbfb8aa3b, v178
	v_mul_f32_e32 v174, 0xbfb8aa3b, v174
	v_mul_f32_e32 v179, 0xbfb8aa3b, v179
	v_mul_f32_e32 v175, 0xbfb8aa3b, v175
	v_mul_f32_e32 v180, 0xbfb8aa3b, v180
	v_mul_f32_e32 v176, 0xbfb8aa3b, v176
	v_mul_f32_e32 v181, 0xbfb8aa3b, v181
	v_mul_f32_e32 v177, 0xbfb8aa3b, v177
	v_exp_f32_e32 v178, v178
	v_exp_f32_e32 v174, v174
	v_exp_f32_e32 v179, v179
	v_exp_f32_e32 v175, v175
	v_exp_f32_e32 v180, v180
	v_exp_f32_e32 v176, v176
	v_exp_f32_e32 v181, v181
	v_exp_f32_e32 v177, v177
	v_add_f32_e32 v178, 1.0, v178
	v_add_f32_e32 v174, 1.0, v174
	v_add_f32_e32 v179, 1.0, v179
	v_add_f32_e32 v175, 1.0, v175
	v_add_f32_e32 v180, 1.0, v180
	v_add_f32_e32 v176, 1.0, v176
	v_add_f32_e32 v181, 1.0, v181
	v_add_f32_e32 v177, 1.0, v177
	v_rcp_f32_e32 v178, v178
	v_rcp_f32_e32 v174, v174
	v_rcp_f32_e32 v179, v179
	v_rcp_f32_e32 v175, v175
	v_rcp_f32_e32 v180, v180
	v_rcp_f32_e32 v176, v176
	v_rcp_f32_e32 v181, v181
	v_rcp_f32_e32 v177, v177
	s_nop 0
	v_mul_f32_e32 v186, v4, v178
	v_mul_f32_e32 v187, v5, v174
	v_mul_f32_e32 v188, v6, v179
	v_mul_f32_e32 v189, v7, v175
	v_mul_f32_e32 v190, v0, v180
	v_mul_f32_e32 v191, v1, v176
	v_mul_f32_e32 v192, v2, v181
	v_mul_f32_e32 v193, v3, v177
	v_cvt_pk_bf16_f32 v174, v186, v187
	v_cvt_pk_bf16_f32 v175, v188, v189
	v_cvt_pk_bf16_f32 v176, v190, v191
	v_cvt_pk_bf16_f32 v177, v192, v193
	global_store_dwordx4 v[210:211], v[174:177], off offset:256
	v_readlane_b32 s98, v254, 40
	s_nop 3
	s_cmp_lg_u32 s98, 0
	s_cbranch_scc1 .Lmgepi_done
	s_cmp_lg_u32 s86, 0x100
	s_cbranch_scc1 .Lmgepi_done
	s_waitcnt vmcnt(0)
	s_mov_b64 s[6:7], exec
	s_mov_b64 exec, 1
	v_mov_b32_e32 v178, 0x22320
	v_mov_b32_e32 v179, 1
	ds_add_rtn_u32 v178, v178, v179
	s_waitcnt lgkmcnt(0)
	v_readfirstlane_b32 s98, v178
	s_and_b32 s98, s98, 7
	s_cmp_lg_u32 s98, 7
	s_cbranch_scc1 .Lmgepi_pub_skip
	v_readlane_b32 s98, v255, 30
	s_nop 3
	s_cmp_lg_u32 s98, 0
	s_cselect_b32 s100, 0x200, 0
	s_cmp_ge_u32 s58, 6
	s_cbranch_scc1 .Lmgepi_pub_r2
	s_lshr_b32 s101, s100, 7
	v_readlane_b32 s98, v253, 3
	v_readlane_b32 s99, v253, 4
	s_nop 3
	s_add_u32 s98, s98, s101
	s_addc_u32 s99, s99, 0
	s_nop 4
	global_atomic_add v178, v113, v179, s[98:99] offset:64 sc0
	v_mov_b32_e32 v180, 0x22300
	ds_read_b32 v180, v180
	s_waitcnt vmcnt(0) lgkmcnt(0)
	v_add_u32_e32 v178, 1, v178
	v_cmp_eq_u32_e32 vcc, v178, v180
	s_cbranch_vccz .Lmgepi_pub_skip
	buffer_wbl2 sc1
	s_waitcnt vmcnt(0)
	s_add_u32 s100, s100, 0x8000
	s_add_u32 s98, s88, s100
	s_addc_u32 s99, s89, 0
	s_nop 4
	global_atomic_add v113, v179, s[98:99]
	s_branch .Lmgepi_pub_skip

.LBB0_1491:
	s_waitcnt vmcnt(0)
	s_waitcnt lgkmcnt(0)
	s_barrier
	v_readlane_b32 s98, v254, 40
	s_nop 3
	s_cmp_lg_u32 s98, 0
	s_cbranch_scc1 .Lmg_gsync_do
	s_cmp_lg_u32 s86, 0x100
	s_cbranch_scc1 .Lmg_gsync_do
	s_mov_b64 s[2:3], exec
	v_readlane_b32 s30, v254, 42
	v_readlane_b32 s31, v254, 43
	s_branch .LBB0_1543

.LBB0_1547:
	v_readlane_b32 s98, v255, 12
	v_readlane_b32 s99, v255, 13
	s_nop 1
	v_writelane_b32 v255, s98, 52
	v_writelane_b32 v255, s99, 53
	v_readlane_b32 s98, v255, 15
	v_readlane_b32 s99, v255, 16
	s_nop 1
	v_writelane_b32 v255, s98, 54
	v_writelane_b32 v255, s99, 55
	v_readlane_b32 s98, v255, 8
	s_nop 1
	v_writelane_b32 v255, s98, 56
	v_writelane_b32 v255, s82, 57
	v_writelane_b32 v255, s86, 58
	v_readlane_b32 s98, v254, 40
	s_nop 3
	s_cmp_lg_u32 s98, 0
	s_cbranch_scc1 .Lwo_sched_done
	s_cmp_lg_u32 s86, 0x100
	s_cbranch_scc1 .Lwo_sched_done
	s_mov_b32 s39, s82
	s_cmp_lt_u32 s82, 16
	s_cbranch_scc1 .Lwo_sched_lo
	s_sub_u32 s82, s82, 16
	s_movk_i32 s86, 0xf0
	s_movk_i32 s7, 0x100
	s_branch .Lwo_sched_set
